# v53 + even out-proj epilogue: first-group wait split (vmcnt 14 then 12) and path-specific group-2 waits (14 on the bf16-copy path, 12 on the plain path)
# baseline (speedup 1.0000x reference)
; __device__ __forceinline__ u32x4 pack8(f32x4 a, f32x4 b) { u32x4 w; w.x = cvt_pk_bf16(a[0], a[1]); w.y = cvt_pk_bf16(a[2], a[3]); w.z = cvt_pk_bf16(b[0], b[1]); w.w = cvt_pk_bf16(b[2], b[3]); return w; }
; __device__ __forceinline__ float sq4(f32x4 a) { return (a[0] * a[0] + a[1] * a[1]) + (a[2] * a[2] + a[3] * a[3]); }
;     __device__ __forceinline__ void load2(f32x4 (&xv)[2][2][2], const float* rb, int b) const {
; #pragma unroll
;         for (int mm = 0; mm < 2; ++mm) {
;             const float* xp = rb + (size_t)((b >> 1) * HALF + (2 * (b & 1) + mm) * 16) * DM;
; #pragma unroll
;             for (int bj = 0; bj < 2; ++bj) { xv[mm][bj][0] = *(const f32x4*)(xp + bj * HALF); xv[mm][bj][1] = *(const f32x4*)(xp + bj * HALF + 4); }
;         }
;     }
;     __device__ __forceinline__ void operator()(const f32x4 (&acc)[2][2][4][2], const Unit& u, int wr, int wc, int fr_, int fq_, int slot) const {
;         int fr = fr_, fq = fq_; asm volatile("" : "+v"(fr), "+v"(fq));
;         const int pn = u.pn, col0 = pn * BM + wc * 32 + 8 * fq;
;         const float* rb = ((u.pm * BM < MPROMPT) ? R0 : R1) + (size_t)(u.pm * BM + wr * 64 + fr) * DM + col0;
;         f32x4 xa[2][2][2], xb2[2][2][2];
;         load2(xa, rb, 0);
; #pragma unroll
;         for (int b = 0; b < 4; ++b) {
;             if (b + 1 < 4) { if (b & 1) load2(xa, rb, b + 1); else load2(xb2, rb, b + 1); }
;             const int ai = b >> 1;
; #pragma unroll
;             for (int mm = 0; mm < 2; ++mm) {
;                 const int m = 2 * (b & 1) + mm;
;                 const int row = u.pm * BM + ai * HALF + wr * 64 + m * 16 + fr;
;                 float* xp = X + (size_t)row * DM + col0; bf16_t* bp = XB + (size_t)row * DM + col0;
;                 float sq = 0.f;
; #pragma unroll
;                 for (int bj = 0; bj < 2; ++bj) {
;                     const f32x4 x0 = ((b & 1) ? xb2[mm][bj][0] : xa[mm][bj][0]) + acc[ai][bj][m][0], x1 = ((b & 1) ? xb2[mm][bj][1] : xa[mm][bj][1]) + acc[ai][bj][m][1];
;                     if (!dry) { *(f32x4*)(xp + bj * HALF) = x0; *(f32x4*)(xp + bj * HALF + 4) = x1;
;                     if (!lastl) *(u32x4*)(bp + bj * HALF) = pack8(x0, x1); }
;                     sq += sq4(x0) + sq4(x1);
;                 }
;                 if (!lastl) { sq = fq_sum(sq); if (fq == 0 && !dry) ss[(size_t)row * 16 + pn * 4 + wc] = sq; }
.LBB0_163:
	s_lshl_b32 s8, s44, 8
	v_mov_b32_e32 v122, v234
	v_mov_b32_e32 v126, v235
	s_or_b32 s8, s8, s23
	s_lshl_b32 s94, s44, 2
	v_lshl_add_u32 v210, v126, 3, s8
	s_lshl_b32 s8, s22, 8
	s_add_i32 s8, s8, s99
	v_add_u32_e32 v212, s8, v122
	v_ashrrev_i32_e32 v213, 31, v212
	v_lshlrev_b64 v[122:123], 12, v[212:213]
	v_lshl_add_u64 v[122:123], s[78:79], 0, v[122:123]
	v_ashrrev_i32_e32 v211, 31, v210
	v_lshl_add_u64 v[214:215], v[210:211], 2, v[122:123]
	s_mov_b64 s[8:9], 0x10000
	v_lshl_add_u64 v[122:123], v[214:215], 0, s[8:9]
	s_mov_b32 s8, 0x10000
	v_add_co_u32_e32 v124, vcc, s8, v214
	s_mov_b64 s[8:9], 0x10200
	s_nop 0
	v_addc_co_u32_e32 v125, vcc, 0, v215, vcc
	global_load_dwordx4 v[186:189], v[214:215], off offset:16
	global_load_dwordx4 v[190:193], v[214:215], off
	global_load_dwordx4 v[178:181], v[214:215], off offset:528
	global_load_dwordx4 v[182:185], v[214:215], off offset:512
	global_load_dwordx4 v[174:177], v[124:125], off
	global_load_dwordx4 v[170:173], v[122:123], off offset:16
	v_lshl_add_u64 v[122:123], v[214:215], 0, s[8:9]
	s_mov_b64 s[8:9], 0x20000
	global_load_dwordx4 v[166:169], v[124:125], off offset:512
	global_load_dwordx4 v[162:165], v[122:123], off offset:16
	v_lshl_add_u64 v[122:123], v[214:215], 0, s[8:9]
	s_mov_b32 s8, 0x20000
	v_add_co_u32_e32 v124, vcc, s8, v214
	s_mov_b64 s[8:9], 0x20200
	s_nop 0
	v_addc_co_u32_e32 v125, vcc, 0, v215, vcc
	global_load_dwordx4 v[158:161], v[124:125], off
	global_load_dwordx4 v[154:157], v[122:123], off offset:16
	v_lshl_add_u64 v[122:123], v[214:215], 0, s[8:9]
	s_mov_b64 s[8:9], 0x30000
	global_load_dwordx4 v[150:153], v[124:125], off offset:512
	global_load_dwordx4 v[146:149], v[122:123], off offset:16
	v_lshl_add_u64 v[122:123], v[214:215], 0, s[8:9]
	s_mov_b32 s8, 0x30000
	v_add_co_u32_e32 v124, vcc, s8, v214
	s_mov_b64 s[8:9], 0x30200
	s_nop 0
	v_addc_co_u32_e32 v125, vcc, 0, v215, vcc
	global_load_dwordx4 v[142:145], v[124:125], off
	global_load_dwordx4 v[138:141], v[122:123], off offset:16
	v_lshl_add_u64 v[122:123], v[214:215], 0, s[8:9]
	v_cmp_eq_u32_e64 s[42:43], 0, v126
	global_load_dwordx4 v[126:129], v[124:125], off offset:512
	s_nop 0
	global_load_dwordx4 v[122:125], v[122:123], off offset:16
	s_ashr_i32 s95, s94, 31
	s_mov_b64 s[92:93], -1
	s_andn2_b64 vcc, exec, s[84:85]
	s_waitcnt vmcnt(14)
	v_pk_add_f32 v[190:191], v[134:135], v[190:191]
	v_pk_add_f32 v[134:135], v[130:131], v[186:187]
	v_cndmask_b32_e64 v130, 0, 1, s[84:85]
	v_pk_add_f32 v[192:193], v[136:137], v[192:193]
	v_pk_add_f32 v[136:137], v[132:133], v[188:189]
	v_cmp_ne_u32_e64 s[44:45], 1, v130
	s_waitcnt vmcnt(12)
	v_pk_add_f32 v[130:131], v[118:119], v[182:183]
	v_pk_add_f32 v[186:187], v[114:115], v[178:179]
	global_store_dwordx4 v[214:215], v[190:193], off
	global_store_dwordx4 v[214:215], v[134:137], off offset:16
	s_cbranch_vccnz .LBB0_167
	v_mul_f32_e32 v118, v191, v191
	v_mul_f32_e32 v119, v193, v193
	v_fmac_f32_e32 v118, v190, v190
	v_fmac_f32_e32 v119, v192, v192
	v_lshlrev_b64 v[114:115], 11, v[212:213]
	v_add_f32_e32 v118, v118, v119
	v_mul_f32_e32 v119, v135, v135
	v_lshl_add_u64 v[114:115], s[6:7], 0, v[114:115]
	v_cvt_pk_bf16_f32 v248, v190, v191
	v_cvt_pk_bf16_f32 v249, v192, v193
	v_cvt_pk_bf16_f32 v250, v134, v135
	v_fmac_f32_e32 v119, v134, v134
	v_mul_f32_e32 v134, v137, v137
	v_lshl_add_u64 v[114:115], v[210:211], 1, v[114:115]
	v_pk_add_f32 v[132:133], v[120:121], v[184:185]
	v_fmac_f32_e32 v134, v136, v136
	v_cvt_pk_bf16_f32 v251, v136, v137
	global_store_dwordx4 v[114:115], v[248:251], off
	v_pk_add_f32 v[188:189], v[116:117], v[180:181]
	global_store_dwordx4 v[214:215], v[130:133], off offset:512
	global_store_dwordx4 v[214:215], v[186:189], off offset:528
	v_add_f32_e32 v119, v119, v134
	v_cvt_pk_bf16_f32 v134, v130, v131
	v_cvt_pk_bf16_f32 v135, v132, v133
	v_cvt_pk_bf16_f32 v136, v186, v187
	v_cvt_pk_bf16_f32 v137, v188, v189
	global_store_dwordx4 v[114:115], v[134:137], off offset:256
	v_mul_f32_e32 v114, v131, v131
	v_mul_f32_e32 v115, v133, v133
	v_fmac_f32_e32 v114, v130, v130
	v_fmac_f32_e32 v115, v132, v132
	v_add_f32_e32 v118, v118, v119
	v_add_f32_e32 v114, v114, v115
	v_mul_f32_e32 v115, v187, v187
	v_mul_f32_e32 v119, v189, v189
	v_fmac_f32_e32 v115, v186, v186
	v_fmac_f32_e32 v119, v188, v188
	v_add_f32_e32 v115, v115, v119
	v_add_f32_e32 v114, v114, v115
	v_add_f32_e32 v114, v118, v114
	v_mov_b32_e32 v115, v114
	s_nop 1
	v_permlane16_swap_b32_e32 v114, v115
	v_add_f32_e32 v114, v114, v115
	v_mov_b32_e32 v115, v114
	s_nop 1
	v_permlane32_swap_b32_e32 v114, v115
	s_and_saveexec_b64 s[92:93], s[42:43]
	s_cbranch_execz .LBB0_166
	v_lshlrev_b64 v[118:119], 6, v[212:213]
	v_lshl_add_u64 v[118:119], s[96:97], 0, v[118:119]
	v_lshl_add_u64 v[118:119], s[94:95], 2, v[118:119]
	s_lshl_b32 s46, s98, 2
	v_lshl_add_u64 v[118:119], v[118:119], 0, s[46:47]
	v_add_f32_e32 v114, v114, v115
	global_store_dword v[118:119], v114, off
.LBB0_166:
	s_or_b64 exec, exec, s[92:93]
	s_mov_b64 s[92:93], 0
	s_waitcnt vmcnt(14)
.LBB0_167:
	s_andn2_b64 vcc, exec, s[92:93]
	s_cbranch_vccnz .LBB0_169
	v_pk_add_f32 v[132:133], v[120:121], v[184:185]
	v_pk_add_f32 v[188:189], v[116:117], v[180:181]
	global_store_dwordx4 v[214:215], v[130:133], off offset:512
	global_store_dwordx4 v[214:215], v[186:189], off offset:528
	s_waitcnt vmcnt(12)
